# stacked: PREP x->bf16 conversion loop software-pipelined (8 loads in flight per thread) on top of the previous version
# baseline (speedup 1.0000x reference)
.LBB0_38:
	s_cmp_lt_u32 s2, s0
	s_cselect_b32 s3, 12, 18
	s_add_u32 s4, s10, s3
	s_addc_u32 s5, s11, 0
	v_mov_b32_e32 v1, 0
	global_load_ushort v1, v1, s[4:5]
	s_waitcnt vmcnt(0)
	v_readfirstlane_b32 s3, v1
	v_and_b32_e32 v1, 0xffff, v1
	v_mad_u64_u32 v[4:5], s[4:5], v1, s2, v[160:161]
	s_mov_b64 s[4:5], 0x400000
	s_nop 0
	v_cmp_gt_u64_e32 vcc, s[4:5], v[4:5]
	s_and_saveexec_b64 s[4:5], vcc
	s_cbranch_execz .LBB0_41
	s_load_dwordx16 s[16:31], s[96:97], 0x0
	s_and_b32 s6, s3, 0xffff
	v_lshlrev_b64 v[6:7], 5, v[4:5]
	s_mul_hi_u32 s7, s6, s0
	s_mul_i32 s6, s6, s0
	s_waitcnt lgkmcnt(0)
	v_lshl_add_u64 v[6:7], s[16:17], 0, v[6:7]
	v_lshl_add_u64 v[8:9], v[4:5], 4, s[86:87]
	s_mov_b64 s[14:15], 0x4000000
	v_lshl_add_u64 v[6:7], v[6:7], 0, 16
	s_lshl_b64 s[8:9], s[6:7], 5
	v_lshl_add_u64 v[8:9], v[8:9], 0, s[14:15]
	s_lshl_b64 s[14:15], s[6:7], 4
	s_mov_b64 s[16:17], 0
	s_mov_b64 s[18:19], 0x3fffff
	s_cmp_eq_u32 s6, 0x20000
	s_cbranch_scc0 .LBB0_40
	s_cmp_eq_u32 s7, 0
	s_cbranch_scc0 .LBB0_40
	global_load_dwordx4 v[64:67], v[6:7], off offset:-16
	global_load_dwordx4 v[68:71], v[6:7], off
	v_lshl_add_u64 v[6:7], v[6:7], 0, s[8:9]
	global_load_dwordx4 v[72:75], v[6:7], off offset:-16
	global_load_dwordx4 v[76:79], v[6:7], off
	v_lshl_add_u64 v[6:7], v[6:7], 0, s[8:9]
	global_load_dwordx4 v[80:83], v[6:7], off offset:-16
	global_load_dwordx4 v[84:87], v[6:7], off
	v_lshl_add_u64 v[6:7], v[6:7], 0, s[8:9]
	global_load_dwordx4 v[88:91], v[6:7], off offset:-16
	global_load_dwordx4 v[92:95], v[6:7], off
	v_lshl_add_u64 v[6:7], v[6:7], 0, s[8:9]
	s_mov_b32 s16, 0
.Lxb_loop:
	global_load_dwordx4 v[96:99], v[6:7], off offset:-16
	global_load_dwordx4 v[100:103], v[6:7], off
	v_lshl_add_u64 v[6:7], v[6:7], 0, s[8:9]
	global_load_dwordx4 v[104:107], v[6:7], off offset:-16
	global_load_dwordx4 v[108:111], v[6:7], off
	v_lshl_add_u64 v[6:7], v[6:7], 0, s[8:9]
	global_load_dwordx4 v[112:115], v[6:7], off offset:-16
	global_load_dwordx4 v[116:119], v[6:7], off
	v_lshl_add_u64 v[6:7], v[6:7], 0, s[8:9]
	global_load_dwordx4 v[120:123], v[6:7], off offset:-16
	global_load_dwordx4 v[124:127], v[6:7], off
	v_lshl_add_u64 v[6:7], v[6:7], 0, s[8:9]
	s_waitcnt vmcnt(14)
	v_cvt_pk_bf16_f32 v128, v64, v65
	v_cvt_pk_bf16_f32 v129, v66, v67
	v_cvt_pk_bf16_f32 v130, v68, v69
	v_cvt_pk_bf16_f32 v131, v70, v71
	global_store_dwordx4 v[8:9], v[128:131], off
	v_lshl_add_u64 v[8:9], v[8:9], 0, s[14:15]
	s_waitcnt vmcnt(13)
	v_cvt_pk_bf16_f32 v132, v72, v73
	v_cvt_pk_bf16_f32 v133, v74, v75
	v_cvt_pk_bf16_f32 v134, v76, v77
	v_cvt_pk_bf16_f32 v135, v78, v79
	global_store_dwordx4 v[8:9], v[132:135], off
	v_lshl_add_u64 v[8:9], v[8:9], 0, s[14:15]
	s_waitcnt vmcnt(12)
	v_cvt_pk_bf16_f32 v136, v80, v81
	v_cvt_pk_bf16_f32 v137, v82, v83
	v_cvt_pk_bf16_f32 v138, v84, v85
	v_cvt_pk_bf16_f32 v139, v86, v87
	global_store_dwordx4 v[8:9], v[136:139], off
	v_lshl_add_u64 v[8:9], v[8:9], 0, s[14:15]
	s_waitcnt vmcnt(11)
	v_cvt_pk_bf16_f32 v140, v88, v89
	v_cvt_pk_bf16_f32 v141, v90, v91
	v_cvt_pk_bf16_f32 v142, v92, v93
	v_cvt_pk_bf16_f32 v143, v94, v95
	global_store_dwordx4 v[8:9], v[140:143], off
	v_lshl_add_u64 v[8:9], v[8:9], 0, s[14:15]
	global_load_dwordx4 v[64:67], v[6:7], off offset:-16
	global_load_dwordx4 v[68:71], v[6:7], off
	v_lshl_add_u64 v[6:7], v[6:7], 0, s[8:9]
	global_load_dwordx4 v[72:75], v[6:7], off offset:-16
	global_load_dwordx4 v[76:79], v[6:7], off
	v_lshl_add_u64 v[6:7], v[6:7], 0, s[8:9]
	global_load_dwordx4 v[80:83], v[6:7], off offset:-16
	global_load_dwordx4 v[84:87], v[6:7], off
	v_lshl_add_u64 v[6:7], v[6:7], 0, s[8:9]
	global_load_dwordx4 v[88:91], v[6:7], off offset:-16
	global_load_dwordx4 v[92:95], v[6:7], off
	v_lshl_add_u64 v[6:7], v[6:7], 0, s[8:9]
	s_waitcnt vmcnt(14)
	v_cvt_pk_bf16_f32 v128, v96, v97
	v_cvt_pk_bf16_f32 v129, v98, v99
	v_cvt_pk_bf16_f32 v130, v100, v101
	v_cvt_pk_bf16_f32 v131, v102, v103
	global_store_dwordx4 v[8:9], v[128:131], off
	v_lshl_add_u64 v[8:9], v[8:9], 0, s[14:15]
	s_waitcnt vmcnt(13)
	v_cvt_pk_bf16_f32 v132, v104, v105
	v_cvt_pk_bf16_f32 v133, v106, v107
	v_cvt_pk_bf16_f32 v134, v108, v109
	v_cvt_pk_bf16_f32 v135, v110, v111
	global_store_dwordx4 v[8:9], v[132:135], off
	v_lshl_add_u64 v[8:9], v[8:9], 0, s[14:15]
	s_waitcnt vmcnt(12)
	v_cvt_pk_bf16_f32 v136, v112, v113
	v_cvt_pk_bf16_f32 v137, v114, v115
	v_cvt_pk_bf16_f32 v138, v116, v117
	v_cvt_pk_bf16_f32 v139, v118, v119
	global_store_dwordx4 v[8:9], v[136:139], off
	v_lshl_add_u64 v[8:9], v[8:9], 0, s[14:15]
	s_waitcnt vmcnt(11)
	v_cvt_pk_bf16_f32 v140, v120, v121
	v_cvt_pk_bf16_f32 v141, v122, v123
	v_cvt_pk_bf16_f32 v142, v124, v125
	v_cvt_pk_bf16_f32 v143, v126, v127
	global_store_dwordx4 v[8:9], v[140:143], off
	v_lshl_add_u64 v[8:9], v[8:9], 0, s[14:15]
	s_add_u32 s16, s16, 1
	s_cmp_lt_u32 s16, 3
	s_cbranch_scc1 .Lxb_loop
	global_load_dwordx4 v[96:99], v[6:7], off offset:-16
	global_load_dwordx4 v[100:103], v[6:7], off
	v_lshl_add_u64 v[6:7], v[6:7], 0, s[8:9]
	global_load_dwordx4 v[104:107], v[6:7], off offset:-16
	global_load_dwordx4 v[108:111], v[6:7], off
	v_lshl_add_u64 v[6:7], v[6:7], 0, s[8:9]
	global_load_dwordx4 v[112:115], v[6:7], off offset:-16
	global_load_dwordx4 v[116:119], v[6:7], off
	v_lshl_add_u64 v[6:7], v[6:7], 0, s[8:9]
	global_load_dwordx4 v[120:123], v[6:7], off offset:-16
	global_load_dwordx4 v[124:127], v[6:7], off
	v_lshl_add_u64 v[6:7], v[6:7], 0, s[8:9]
	s_waitcnt vmcnt(14)
	v_cvt_pk_bf16_f32 v128, v64, v65
	v_cvt_pk_bf16_f32 v129, v66, v67
	v_cvt_pk_bf16_f32 v130, v68, v69
	v_cvt_pk_bf16_f32 v131, v70, v71
	global_store_dwordx4 v[8:9], v[128:131], off
	v_lshl_add_u64 v[8:9], v[8:9], 0, s[14:15]
	s_waitcnt vmcnt(13)
	v_cvt_pk_bf16_f32 v132, v72, v73
	v_cvt_pk_bf16_f32 v133, v74, v75
	v_cvt_pk_bf16_f32 v134, v76, v77
	v_cvt_pk_bf16_f32 v135, v78, v79
	global_store_dwordx4 v[8:9], v[132:135], off
	v_lshl_add_u64 v[8:9], v[8:9], 0, s[14:15]
	s_waitcnt vmcnt(12)
	v_cvt_pk_bf16_f32 v136, v80, v81
	v_cvt_pk_bf16_f32 v137, v82, v83
	v_cvt_pk_bf16_f32 v138, v84, v85
	v_cvt_pk_bf16_f32 v139, v86, v87
	global_store_dwordx4 v[8:9], v[136:139], off
	v_lshl_add_u64 v[8:9], v[8:9], 0, s[14:15]
	s_waitcnt vmcnt(11)
	v_cvt_pk_bf16_f32 v140, v88, v89
	v_cvt_pk_bf16_f32 v141, v90, v91
	v_cvt_pk_bf16_f32 v142, v92, v93
	v_cvt_pk_bf16_f32 v143, v94, v95
	global_store_dwordx4 v[8:9], v[140:143], off
	v_lshl_add_u64 v[8:9], v[8:9], 0, s[14:15]
	s_waitcnt vmcnt(10)
	v_cvt_pk_bf16_f32 v128, v96, v97
	v_cvt_pk_bf16_f32 v129, v98, v99
	v_cvt_pk_bf16_f32 v130, v100, v101
	v_cvt_pk_bf16_f32 v131, v102, v103
	global_store_dwordx4 v[8:9], v[128:131], off
	v_lshl_add_u64 v[8:9], v[8:9], 0, s[14:15]
	s_waitcnt vmcnt(9)
	v_cvt_pk_bf16_f32 v132, v104, v105
	v_cvt_pk_bf16_f32 v133, v106, v107
	v_cvt_pk_bf16_f32 v134, v108, v109
	v_cvt_pk_bf16_f32 v135, v110, v111
	global_store_dwordx4 v[8:9], v[132:135], off
	v_lshl_add_u64 v[8:9], v[8:9], 0, s[14:15]
	s_waitcnt vmcnt(8)
	v_cvt_pk_bf16_f32 v136, v112, v113
	v_cvt_pk_bf16_f32 v137, v114, v115
	v_cvt_pk_bf16_f32 v138, v116, v117
	v_cvt_pk_bf16_f32 v139, v118, v119
	global_store_dwordx4 v[8:9], v[136:139], off
	v_lshl_add_u64 v[8:9], v[8:9], 0, s[14:15]
	s_waitcnt vmcnt(7)
	v_cvt_pk_bf16_f32 v140, v120, v121
	v_cvt_pk_bf16_f32 v141, v122, v123
	v_cvt_pk_bf16_f32 v142, v124, v125
	v_cvt_pk_bf16_f32 v143, v126, v127
	global_store_dwordx4 v[8:9], v[140:143], off
	v_lshl_add_u64 v[8:9], v[8:9], 0, s[14:15]
	s_branch .LBB0_41
